# norm phase bf16 path: 4 serialized row-load drains merged into one counted wait, shift/scale lines prefetched behind them
# baseline (speedup 1.0000x reference)
.LBB0_1485:
	v_cmp_gt_i32_e64 s[38:39], s92, v106
	s_mov_b64 s[40:41], -1
	s_and_b64 vcc, exec, s[22:23]
	v_ashrrev_i32_e32 v107, 31, v106
	s_cbranch_vccz .LBB0_1487
	v_lshlrev_b64 v[18:19], 11, v[106:107]
	v_lshl_add_u64 v[22:23], v[110:111], 0, v[18:19]
	global_load_dwordx4 v[18:21], v[22:23], off
	s_nop 0
	global_load_dwordx4 v[22:25], v[22:23], off offset:1024
	s_mov_b64 s[40:41], 0
.LBB0_1487:
	v_add_u32_e32 v82, 0xffffe000, v106
	s_andn2_b64 vcc, exec, s[40:41]
	v_lshlrev_b32_e32 v0, 2, v108
	s_cbranch_vccnz .LBB0_1489
	v_readlane_b32 s24, v254, 6
	v_readlane_b32 s25, v254, 7
	v_readlane_b32 s27, v254, 9
	v_readlane_b32 s26, v254, 8
	v_mov_b32_e32 v21, s25
	v_mov_b32_e32 v20, s27
	v_cndmask_b32_e64 v19, 0, v107, s[38:39]
	v_cndmask_b32_e64 v18, v82, v106, s[38:39]
	v_cndmask_b32_e64 v21, v20, v21, s[38:39]
	v_mov_b32_e32 v20, s26
	v_mov_b32_e32 v22, s24
	v_cndmask_b32_e64 v20, v20, v22, s[38:39]
	v_lshlrev_b64 v[18:19], 12, v[18:19]
	v_lshl_add_u64 v[18:19], v[20:21], 0, v[18:19]
	v_lshl_add_u64 v[18:19], v[18:19], 0, v[0:1]
	global_load_dwordx4 v[38:41], v[18:19], off offset:16
	global_load_dwordx4 v[34:37], v[18:19], off
	global_load_dwordx4 v[22:25], v[18:19], off offset:2064
	s_nop 0
	global_load_dwordx4 v[18:21], v[18:19], off offset:2048
.LBB0_1489:
	v_add_u32_e32 v114, 1, v106
	v_cndmask_b32_e64 v26, 0, 1, s[22:23]
	s_mov_b64 s[44:45], -1
	v_cmp_ne_u32_e64 s[40:41], 1, v26
	s_andn2_b64 vcc, exec, s[22:23]
	v_ashrrev_i32_e32 v115, 31, v114
	s_cbranch_vccnz .LBB0_1491
	v_lshlrev_b64 v[26:27], 11, v[114:115]
	v_lshl_add_u64 v[30:31], v[110:111], 0, v[26:27]
	global_load_dwordx4 v[26:29], v[30:31], off
	s_nop 0
	global_load_dwordx4 v[30:33], v[30:31], off offset:1024
	s_mov_b64 s[44:45], 0
.LBB0_1491:
	s_andn2_b64 vcc, exec, s[44:45]
	s_cbranch_vccnz .LBB0_1493
	v_readlane_b32 s24, v254, 6
	v_readlane_b32 s25, v254, 7
	v_readlane_b32 s27, v254, 9
	v_add_u32_e32 v26, 0xffffe001, v106
	v_cmp_gt_i32_e32 vcc, s92, v114
	v_readlane_b32 s26, v254, 8
	v_mov_b32_e32 v28, s27
	v_mov_b32_e32 v29, s25
	v_cndmask_b32_e32 v27, 0, v115, vcc
	v_cndmask_b32_e32 v26, v26, v114, vcc
	v_cndmask_b32_e32 v29, v28, v29, vcc
	v_mov_b32_e32 v28, s26
	v_mov_b32_e32 v30, s24
	v_cndmask_b32_e32 v28, v28, v30, vcc
	v_lshlrev_b64 v[26:27], 12, v[26:27]
	v_lshl_add_u64 v[26:27], v[28:29], 0, v[26:27]
	v_lshl_add_u64 v[26:27], v[26:27], 0, v[0:1]
	global_load_dwordx4 v[54:57], v[26:27], off offset:16
	global_load_dwordx4 v[46:49], v[26:27], off
	global_load_dwordx4 v[30:33], v[26:27], off offset:2064
	s_nop 0
	global_load_dwordx4 v[26:29], v[26:27], off offset:2048
.LBB0_1493:
	v_add_u32_e32 v116, 2, v106
	s_mov_b64 s[44:45], -1
	s_and_b64 vcc, exec, s[40:41]
	v_ashrrev_i32_e32 v117, 31, v116
	s_cbranch_vccnz .LBB0_1495
	v_lshlrev_b64 v[42:43], 11, v[116:117]
	v_lshl_add_u64 v[50:51], v[110:111], 0, v[42:43]
	global_load_dwordx4 v[42:45], v[50:51], off
	s_nop 0
	global_load_dwordx4 v[50:53], v[50:51], off offset:1024
	s_mov_b64 s[44:45], 0
.LBB0_1495:
	s_andn2_b64 vcc, exec, s[44:45]
	s_cbranch_vccnz .LBB0_1497
	v_readlane_b32 s24, v254, 6
	v_readlane_b32 s25, v254, 7
	v_readlane_b32 s27, v254, 9
	v_add_u32_e32 v42, 0xffffe002, v106
	v_cmp_gt_i32_e32 vcc, s92, v116
	v_readlane_b32 s26, v254, 8
	v_mov_b32_e32 v44, s27
	v_mov_b32_e32 v45, s25
	v_cndmask_b32_e32 v43, 0, v117, vcc
	v_cndmask_b32_e32 v42, v42, v116, vcc
	v_cndmask_b32_e32 v45, v44, v45, vcc
	v_mov_b32_e32 v44, s26
	v_mov_b32_e32 v50, s24
	v_cndmask_b32_e32 v44, v44, v50, vcc
	v_lshlrev_b64 v[42:43], 12, v[42:43]
	v_lshl_add_u64 v[42:43], v[44:45], 0, v[42:43]
	v_lshl_add_u64 v[42:43], v[42:43], 0, v[0:1]
	global_load_dwordx4 v[62:65], v[42:43], off offset:16
	global_load_dwordx4 v[58:61], v[42:43], off
	global_load_dwordx4 v[50:53], v[42:43], off offset:2064
	s_nop 0
	global_load_dwordx4 v[42:45], v[42:43], off offset:2048
.LBB0_1497:
	v_add_u32_e32 v118, 3, v106
	s_mov_b64 s[44:45], -1
	s_and_b64 vcc, exec, s[40:41]
	v_ashrrev_i32_e32 v119, 31, v118
	s_cbranch_vccnz .LBB0_1499
	v_lshlrev_b64 v[66:67], 11, v[118:119]
	v_lshl_add_u64 v[70:71], v[110:111], 0, v[66:67]
	global_load_dwordx4 v[66:69], v[70:71], off
	s_nop 0
	global_load_dwordx4 v[70:73], v[70:71], off offset:1024
	s_mov_b64 s[44:45], 0

.LBB0_1501:
	v_ashrrev_i32_e32 v82, 11, v82
	v_mad_i32_i24 v82, v82, 6, 6
	v_cndmask_b32_e64 v82, v82, 0, s[38:39]
	v_ashrrev_i32_e32 v83, 31, v82
	v_lshlrev_b64 v[82:83], 12, v[82:83]
	v_lshl_add_u64 v[82:83], s[6:7], 0, v[82:83]
	v_lshl_add_u64 v[86:87], v[82:83], 0, v[0:1]
	s_movk_i32 s0, 0x1000
	v_add_co_u32_e32 v82, vcc, s0, v86
	s_mov_b64 s[2:3], 0x1000
	s_nop 0
	v_addc_co_u32_e32 v83, vcc, 0, v87, vcc
	v_lshl_add_u64 v[98:99], v[86:87], 0, s[2:3]
	s_and_b64 vcc, exec, s[22:23]
	s_cbranch_vccz .Lnorm_f32rows
	global_load_dwordx4 v[120:123], v[82:83], off
	global_load_dwordx4 v[124:127], v[98:99], off offset:16
	global_load_dwordx4 v[148:151], v[86:87], off offset:16
	global_load_dwordx4 v[152:155], v[86:87], off
	global_load_dwordx4 v[156:159], v[86:87], off offset:2064
	global_load_dwordx4 v[160:163], v[86:87], off offset:2048
	global_load_dwordx4 v[164:167], v[98:99], off offset:2048
	global_load_dwordx4 v[168:171], v[98:99], off offset:2064
	s_waitcnt vmcnt(8)
	v_lshlrev_b32_e32 v34, 16, v18
	v_and_b32_e32 v35, 0xffff0000, v18
	v_lshlrev_b32_e32 v36, 16, v19
	v_and_b32_e32 v37, 0xffff0000, v19
	v_lshlrev_b32_e32 v38, 16, v20
	v_and_b32_e32 v39, 0xffff0000, v20
	v_lshlrev_b32_e32 v40, 16, v21
	v_and_b32_e32 v41, 0xffff0000, v21
	v_lshlrev_b32_e32 v18, 16, v22
	v_and_b32_e32 v19, 0xffff0000, v22
	v_lshlrev_b32_e32 v20, 16, v23
	v_and_b32_e32 v21, 0xffff0000, v23
	v_lshlrev_b32_e32 v22, 16, v24
	v_and_b32_e32 v23, 0xffff0000, v24
	v_lshlrev_b32_e32 v24, 16, v25
	v_and_b32_e32 v25, 0xffff0000, v25
	v_lshlrev_b32_e32 v46, 16, v26
	v_and_b32_e32 v47, 0xffff0000, v26
	v_lshlrev_b32_e32 v48, 16, v27
	v_and_b32_e32 v49, 0xffff0000, v27
	v_lshlrev_b32_e32 v54, 16, v28
	v_and_b32_e32 v55, 0xffff0000, v28
	v_lshlrev_b32_e32 v56, 16, v29
	v_and_b32_e32 v57, 0xffff0000, v29
	v_lshlrev_b32_e32 v26, 16, v30
	v_and_b32_e32 v27, 0xffff0000, v30
	v_lshlrev_b32_e32 v28, 16, v31
	v_and_b32_e32 v29, 0xffff0000, v31
	v_lshlrev_b32_e32 v30, 16, v32
	v_and_b32_e32 v31, 0xffff0000, v32
	v_lshlrev_b32_e32 v32, 16, v33
	v_and_b32_e32 v33, 0xffff0000, v33
	v_lshlrev_b32_e32 v58, 16, v42
	v_and_b32_e32 v59, 0xffff0000, v42
	v_lshlrev_b32_e32 v60, 16, v43
	v_and_b32_e32 v61, 0xffff0000, v43
	v_lshlrev_b32_e32 v62, 16, v44
	v_and_b32_e32 v63, 0xffff0000, v44
	v_lshlrev_b32_e32 v64, 16, v45
	v_and_b32_e32 v65, 0xffff0000, v45
	v_lshlrev_b32_e32 v42, 16, v50
	v_and_b32_e32 v43, 0xffff0000, v50
	v_lshlrev_b32_e32 v44, 16, v51
	v_and_b32_e32 v45, 0xffff0000, v51
	v_lshlrev_b32_e32 v50, 16, v52
	v_and_b32_e32 v51, 0xffff0000, v52
	v_lshlrev_b32_e32 v52, 16, v53
	v_and_b32_e32 v53, 0xffff0000, v53
	v_lshlrev_b32_e32 v74, 16, v66
	v_and_b32_e32 v75, 0xffff0000, v66
	v_lshlrev_b32_e32 v76, 16, v67
	v_and_b32_e32 v77, 0xffff0000, v67
	v_lshlrev_b32_e32 v78, 16, v68
	v_and_b32_e32 v79, 0xffff0000, v68
	v_lshlrev_b32_e32 v80, 16, v69
	v_and_b32_e32 v81, 0xffff0000, v69
	v_lshlrev_b32_e32 v66, 16, v70
	v_and_b32_e32 v67, 0xffff0000, v70
	v_lshlrev_b32_e32 v68, 16, v71
	v_and_b32_e32 v69, 0xffff0000, v71
	v_lshlrev_b32_e32 v70, 16, v72
	v_and_b32_e32 v71, 0xffff0000, v72
	v_lshlrev_b32_e32 v72, 16, v73
	v_and_b32_e32 v73, 0xffff0000, v73
	s_branch .Lnorm_join
.Lnorm_f32rows:
	s_waitcnt vmcnt(0)
	global_load_dwordx4 v[120:123], v[82:83], off
	global_load_dwordx4 v[124:127], v[98:99], off offset:16
.Lnorm_join:
	v_pk_mul_f32 v[82:83], v[36:37], v[36:37]
	v_pk_mul_f32 v[84:85], v[34:35], v[34:35]
	v_pk_mul_f32 v[88:89], v[40:41], v[40:41]
	v_pk_mul_f32 v[90:91], v[38:39], v[38:39]
	v_pk_mov_b32 v[94:95], v[84:85], v[82:83] op_sel:[1,0]
	v_mov_b32_e32 v85, v83
	v_pk_mov_b32 v[82:83], v[90:91], v[88:89] op_sel:[1,0]
	v_mov_b32_e32 v91, v89
	v_mul_f32_e32 v0, v18, v18
	v_mul_f32_e32 v92, v20, v20
	v_mul_f32_e32 v96, v47, v47
	v_mul_f32_e32 v97, v49, v49
	v_mul_f32_e32 v100, v55, v55
	v_mul_f32_e32 v101, v57, v57
	v_pk_add_f32 v[84:85], v[94:95], v[84:85]
	v_pk_add_f32 v[82:83], v[82:83], v[90:91]
	v_mul_f32_e32 v102, v27, v27
	v_mul_f32_e32 v103, v29, v29
	v_mul_f32_e32 v128, v59, v59
	v_mul_f32_e32 v129, v61, v61
	v_mul_f32_e32 v130, v63, v63
	v_mul_f32_e32 v131, v65, v65
	v_pk_fma_f32 v[88:89], v[18:19], v[18:19], v[0:1] op_sel_hi:[1,1,0]
	v_pk_fma_f32 v[92:93], v[20:21], v[20:21], v[92:93] op_sel_hi:[1,1,0]
	v_fmac_f32_e32 v96, v46, v46
	v_fmac_f32_e32 v97, v48, v48
	v_fmac_f32_e32 v100, v54, v54
	v_fmac_f32_e32 v101, v56, v56
	v_pk_add_f32 v[84:85], v[84:85], v[84:85] op_sel_hi:[0,1]
	v_pk_add_f32 v[82:83], v[82:83], v[82:83] op_sel_hi:[0,1]
	v_mul_f32_e32 v104, v31, v31
	v_mul_f32_e32 v105, v33, v33
	v_mul_f32_e32 v132, v43, v43
	v_mul_f32_e32 v133, v45, v45
	v_fmac_f32_e32 v102, v26, v26
	v_fmac_f32_e32 v103, v28, v28
	v_fmac_f32_e32 v128, v58, v58
	v_fmac_f32_e32 v129, v60, v60
	v_fmac_f32_e32 v130, v62, v62
	v_fmac_f32_e32 v131, v64, v64
	v_mul_f32_e32 v88, v22, v22
	v_mul_f32_e32 v92, v23, v23
	v_add_f32_e32 v0, v96, v97
	v_add_f32_e32 v90, v100, v101
	v_mul_f32_e32 v82, v24, v24
	v_mul_f32_e32 v84, v25, v25
	v_fmac_f32_e32 v104, v30, v30
	v_fmac_f32_e32 v105, v32, v32
	v_fmac_f32_e32 v132, v42, v42
	v_fmac_f32_e32 v133, v44, v44
	v_add_f32_e32 v91, v102, v103
	v_add_f32_e32 v95, v128, v129
	v_add_f32_e32 v96, v130, v131
	v_pk_add_f32 v[88:89], v[88:89], v[92:93]
	v_add_f32_e32 v0, v90, v0
	v_pk_add_f32 v[82:83], v[82:83], v[84:85]
	v_add_f32_e32 v94, v104, v105
	v_add_f32_e32 v97, v132, v133
	v_add_f32_e32 v90, v95, v96
	v_add_f32_e32 v0, v91, v0
	v_pk_add_f32 v[100:101], v[88:89], v[82:83]
	v_add_f32_e32 v130, v90, v97
	v_add_f32_e32 v0, v94, v0
	global_load_dwordx4 v[90:93], v[86:87], off offset:16
	global_load_dwordx4 v[94:97], v[86:87], off
	global_load_dwordx4 v[82:85], v[86:87], off offset:2064
	s_nop 0
	global_load_dwordx4 v[86:89], v[86:87], off offset:2048
	v_add_f32_e32 v131, v100, v101
	global_load_dwordx4 v[102:105], v[98:99], off offset:2048
	s_nop 0
	global_load_dwordx4 v[98:101], v[98:99], off offset:2064
	v_mul_f32_e32 v139, v51, v51
	v_mul_f32_e32 v140, v53, v53
	v_fmac_f32_e32 v139, v50, v50
	v_fmac_f32_e32 v140, v52, v52
	v_mul_f32_e32 v132, v81, v81
	v_fmac_f32_e32 v132, v80, v80
	v_mul_f32_e32 v133, v73, v73
	v_fmac_f32_e32 v133, v72, v72
	s_waitcnt vmcnt(0)
	v_pk_add_f32 v[122:123], v[122:123], 1.0 op_sel_hi:[1,0]
	v_pk_add_f32 v[128:129], v[120:121], 1.0 op_sel_hi:[1,0]
	v_pk_mul_f32 v[120:121], v[8:9], v[122:123]
	v_add_f32_e32 v122, v139, v140
	v_add_f32_e32 v130, v130, v122
	v_mul_f32_e32 v122, v75, v75
	v_mul_f32_e32 v123, v77, v77
	v_fmac_f32_e32 v122, v74, v74
	v_fmac_f32_e32 v123, v76, v76
	v_add_f32_e32 v122, v122, v123
	v_mul_f32_e32 v123, v79, v79
	v_fmac_f32_e32 v123, v78, v78
	v_add_f32_e32 v123, v123, v132
	v_add_f32_e32 v122, v122, v123
	v_mul_f32_e32 v123, v67, v67
	v_mul_f32_e32 v132, v69, v69
	v_fmac_f32_e32 v123, v66, v66
	v_fmac_f32_e32 v132, v68, v68
	v_add_f32_e32 v123, v123, v132
	ds_bpermute_b32 v132, v109, v131
	ds_bpermute_b32 v139, v109, v130
	v_add_f32_e32 v122, v122, v123
	v_mul_f32_e32 v123, v71, v71
	v_fmac_f32_e32 v123, v70, v70
	s_waitcnt lgkmcnt(0)
	v_add_f32_e32 v131, v131, v132
	ds_bpermute_b32 v141, v134, v131
	v_add_f32_e32 v123, v123, v133
	v_add_f32_e32 v133, v122, v123
	v_pk_mul_f32 v[122:123], v[6:7], v[128:129]
	v_add_f32_e32 v128, v130, v139
	s_waitcnt lgkmcnt(0)
	v_add_f32_e32 v130, v131, v141
	ds_bpermute_b32 v139, v135, v130
	ds_bpermute_b32 v132, v109, v0
	ds_bpermute_b32 v140, v109, v133
	v_pk_add_f32 v[126:127], v[126:127], 1.0 op_sel_hi:[1,0]
	s_waitcnt lgkmcnt(2)
	v_add_f32_e32 v130, v130, v139
	s_waitcnt lgkmcnt(1)
	v_add_f32_e32 v0, v0, v132
	s_waitcnt lgkmcnt(0)
	v_add_f32_e32 v129, v133, v140
	ds_bpermute_b32 v141, v136, v130
	ds_bpermute_b32 v131, v134, v0
	ds_bpermute_b32 v132, v134, v128
	ds_bpermute_b32 v133, v134, v129
	s_waitcnt lgkmcnt(3)
	v_add_f32_e32 v130, v130, v141
	s_waitcnt lgkmcnt(2)
	v_add_f32_e32 v0, v0, v131
	s_waitcnt lgkmcnt(1)
	v_add_f32_e32 v131, v128, v132
	s_waitcnt lgkmcnt(0)
	v_add_f32_e32 v132, v129, v133
	ds_bpermute_b32 v141, v137, v130
	ds_bpermute_b32 v133, v135, v0
	ds_bpermute_b32 v139, v135, v131
	ds_bpermute_b32 v140, v135, v132
	v_pk_add_f32 v[128:129], v[124:125], 1.0 op_sel_hi:[1,0]
	s_waitcnt lgkmcnt(3)
	v_add_f32_e32 v130, v130, v141
	s_waitcnt lgkmcnt(2)
	v_add_f32_e32 v0, v0, v133
	s_waitcnt lgkmcnt(1)
	v_add_f32_e32 v131, v131, v139
	s_waitcnt lgkmcnt(0)
	v_add_f32_e32 v132, v132, v140
	ds_bpermute_b32 v143, v138, v130
	ds_bpermute_b32 v133, v136, v0
	ds_bpermute_b32 v139, v136, v131
	ds_bpermute_b32 v140, v136, v132
	v_pk_mul_f32 v[124:125], v[4:5], v[126:127]
	v_pk_mul_f32 v[126:127], v[2:3], v[128:129]
	s_waitcnt lgkmcnt(3)
	v_add_f32_e32 v128, v130, v143
	s_waitcnt lgkmcnt(2)
	v_add_f32_e32 v0, v0, v133
	s_waitcnt lgkmcnt(1)
	v_add_f32_e32 v131, v131, v139
	s_waitcnt lgkmcnt(0)
	v_add_f32_e32 v132, v132, v140
	v_fmamk_f32 v128, v128, 0x3a800000, v248
	ds_bpermute_b32 v133, v137, v0
	ds_bpermute_b32 v139, v137, v131
	ds_bpermute_b32 v141, v137, v132
	v_mul_f32_e32 v129, 0x4b800000, v128
	v_cmp_gt_f32_e32 vcc, s8, v128
	s_waitcnt lgkmcnt(2)
	v_add_f32_e32 v142, v0, v133
	s_waitcnt lgkmcnt(1)
	v_add_f32_e32 v140, v131, v139
	v_cndmask_b32_e32 v128, v128, v129, vcc
	v_rsq_f32_e32 v128, v128
	s_waitcnt lgkmcnt(0)
	v_add_f32_e32 v0, v132, v141
	ds_bpermute_b32 v143, v138, v142
	ds_bpermute_b32 v141, v138, v140
	ds_bpermute_b32 v139, v138, v0
	v_mul_f32_e32 v129, 0x45800000, v128
	v_cndmask_b32_e32 v132, v128, v129, vcc
	v_pk_mul_f32 v[144:145], v[132:133], v[34:35] op_sel_hi:[0,1]
	v_pk_mul_f32 v[146:147], v[132:133], v[36:37] op_sel_hi:[0,1]
	v_pk_mul_f32 v[148:149], v[132:133], v[38:39] op_sel_hi:[0,1]
	v_pk_mul_f32 v[150:151], v[132:133], v[40:41] op_sel_hi:[0,1]
	v_lshlrev_b64 v[128:129], 11, v[106:107]
	v_pk_fma_f32 v[146:147], v[120:121], v[146:147], v[96:97]
	v_pk_fma_f32 v[144:145], v[122:123], v[144:145], v[94:95]
	v_pk_fma_f32 v[150:151], v[124:125], v[150:151], v[92:93]
	v_pk_fma_f32 v[148:149], v[126:127], v[148:149], v[90:91]
	v_cndmask_b32_e64 v107, 0, 1, s[20:21]
	v_lshl_add_u64 v[130:131], v[112:113], 0, v[128:129]
	v_lshl_add_u64 v[128:129], v[110:111], 0, v[128:129]
	v_cvt_pk_bf16_f32 v144, v144, v145
	v_cvt_pk_bf16_f32 v145, v146, v147
	v_cvt_pk_bf16_f32 v146, v148, v149
	v_cvt_pk_bf16_f32 v147, v150, v151
	v_cmp_ne_u32_e64 s[38:39], 1, v107
	s_andn2_b64 vcc, exec, s[20:21]
	global_store_dwordx4 v[130:131], v[144:147], off
	s_cbranch_vccnz .LBB0_1503
	v_cvt_pk_bf16_f32 v34, v34, v35
	v_cvt_pk_bf16_f32 v35, v36, v37
	v_cvt_pk_bf16_f32 v36, v38, v39
	v_cvt_pk_bf16_f32 v37, v40, v41
	global_store_dwordx4 v[128:129], v[34:37], off
